# attention tiles processed newest-first; a tile whose max logit is 153 log2 below the running max for every row skips exp/PV (exact zeros); O rescale skipped when no row max increases (alpha exactly 1)
# speedup vs baseline: 1.0199x; 1.0152x over previous
; __device__ __forceinline__ int get_tid() { int t = threadIdx.x; asm volatile("" : "+v"(t)); return t; }
; __device__ void attn_item(const Params& p, int s_idx, char* smem) {
;     const int qb = 63 - (s_idx >> 5), bh = s_idx & 31, b = bh >> 3, h = bh & 7;
;     const int tid = get_tid(), lane = tid & 63, wid = tid >> 6, ql = lane & 31, hh = lane >> 5;
;     const int qrow = qb * 128 + wid * 32 + ql;
;     const bf16_t* projb = p.proj + (size_t)b * S * NIN;
;     bf16x8 qf[4];
; #pragma unroll
;     for (int kk = 0; kk < 4; ++kk) qf[kk] = *(const bf16x8*)(projb + (size_t)qrow * NIN + h * 64 + kk * 16 + hh * 8);
;     f32x16 O0, O1;
; #pragma unroll
;     for (int i = 0; i < 16; ++i) { O0[i] = 0.f; O1[i] = 0.f; }
;     float mrun = -INFINITY, lsum = 0.f;
;     const int nkt = qb * 2 + 2;
;     const int wave_last = (qb * 128 + wid * 32 + 31) >> 6;
;     const int wave_q0 = qb * 128 + wid * 32;
;     const float sc = 0.125f * LOG2E;
;     struct KV { u32x4 rk[2], rv[2]; float rkb; };
;     KV sa;
;     auto gload = [&](int kt, KV& st) {
; #pragma unroll
;         for (int i = 0; i < 2; ++i) {
;             const int c = tid + 256 * i, key = c >> 3, dc = c & 7;
;             const bf16_t* src = projb + (size_t)(kt * 64 + key) * NIN + h * 64 + dc * 8;
;             st.rk[i] = *(const u32x4*)(src + 512);
;             const int keyv = c & 63, dcv = c >> 6;
;             st.rv[i] = *(const u32x4*)(projb + (size_t)(kt * 64 + keyv) * NIN + 1024 + h * 64 + dcv * 8);
;         }
;         st.rkb = p.kb[(size_t)bh * S + kt * 64 + (tid & 63)];
;     ...
;     gload(0, sa); sstore(0, sa); __syncthreads();
.LBB0_107:
	s_ashr_i32 s12, s15, 5
	s_lshl_b32 s13, s15, 10
	s_sub_i32 s14, 63, s12
	v_mov_b32_e32 v3, v126
	s_and_b32 s13, s13, 0x6000
	s_and_b32 s18, s15, 31
	s_lshl_b32 s12, s14, 7
	v_ashrrev_i32_e32 v143, 6, v3
	s_mul_i32 s16, s13, 0x1410
	v_lshlrev_b32_e32 v96, 5, v143
	s_add_u32 s34, s90, s16
	v_and_b32_e32 v2, 31, v3
	v_add_u32_e32 v144, s12, v96
	s_addc_u32 s35, s91, 0
	s_lshl_b32 s15, s15, 6
	v_or_b32_e32 v98, v144, v2
	s_waitcnt lgkmcnt(0)
	v_mov_b64_e32 v[0:1], s[34:35]
	s_and_b32 s15, s15, 0x1c0
	v_bfe_u32 v4, v3, 5, 1
	v_mad_i64_i32 v[6:7], s[16:17], v98, s29, v[0:1]
	s_lshl_b32 s22, s15, 1
	s_mov_b32 s23, s21
	v_lshl_add_u64 v[6:7], v[6:7], 0, s[22:23]
	v_lshlrev_b32_e32 v112, 4, v4
	v_lshl_add_u64 v[6:7], v[6:7], 0, v[112:113]
	v_ashrrev_i32_e32 v145, 3, v3
	v_lshlrev_b32_e32 v5, 3, v3
	global_load_dwordx4 v[64:67], v[6:7], off
	global_load_dwordx4 v[68:71], v[6:7], off offset:32
	global_load_dwordx4 v[72:75], v[6:7], off offset:64
	global_load_dwordx4 v[76:79], v[6:7], off offset:96
	v_readlane_b32 s98, v165, 2
	v_readlane_b32 s99, v165, 3
	v_readlane_b32 s32, v167, 36
	v_and_b32_e32 v32, 7, v130
	v_bfe_u32 v33, v130, 3, 1
	v_lshlrev_b32_e32 v32, 7, v32
	s_mul_i32 s32, s32, 0xc00
	v_lshl_or_b32 v32, v33, 10, v32
	v_mov_b32_e32 v33, s18
	s_add_i32 s32, s32, 32
	v_and_b32_e32 v33, 7, v33
	v_add_u32_e32 v32, s32, v32
	v_lshl_add_u32 v32, v33, 2, v32
	global_load_dword v34, v32, s[98:99] sc0 sc1
	s_lshl_b32 s32, s18, 15
	v_lshlrev_b32_e32 v35, 8, v130
	v_add_u32_e32 v35, s32, v35
	v_add_u32_e32 v38, 0x4000, v35
	s_lshl_b32 s32, s14, 9
	v_add_u32_e32 v39, s32, v35
	v_lshlrev_b32_e32 v33, 8, v130
	v_sub_u32_e32 v39, v39, v33
	v_readlane_b32 s98, v165, 40
	v_readlane_b32 s99, v165, 41
	s_nop 4
	s_nop 0
	global_load_dword v36, v35, s[98:99] offset:252
	global_load_dword v37, v38, s[98:99] offset:252
	global_load_dword v39, v39, s[98:99]
	s_waitcnt vmcnt(3)
	v_max_u32_dpp v34, v34, v34 quad_perm:[1,0,3,2] row_mask:0xf bank_mask:0xf
	s_nop 1
	v_max_u32_dpp v34, v34, v34 quad_perm:[2,3,0,1] row_mask:0xf bank_mask:0xf
	s_nop 1
	v_max_u32_dpp v34, v34, v34 row_half_mirror row_mask:0xf bank_mask:0xf
	s_waitcnt vmcnt(0)
	s_nop 0
	v_readlane_b32 s98, v34, 0
	v_readlane_b32 s99, v34, 8
	v_mov_b32_e32 v41, 0xbeb908c8
	s_nop 0
	v_mov_b32_e32 v40, s98
	v_mul_f32_e32 v40, s99, v40
	v_sqrt_f32_e32 v40, v40
	s_nop 0
	v_fma_f32 v40, v40, v41, v39
	v_add_f32_e32 v40, 0xc31b0000, v40
	v_cmp_lt_f32_e32 vcc, v36, v40
	s_bcnt1_i32_b64 s32, vcc
	v_cmp_lt_f32_e32 vcc, v37, v40
	s_bcnt1_i32_b64 s98, vcc
	s_add_i32 s32, s32, s98
	s_lshl_b32 s98, s14, 1
	s_min_i32 s32, s32, s98
	s_and_b32 s32, s32, -2
	s_lshl_b32 s98, s32, 6
	s_lshl_b32 s99, s14, 7
	s_add_i32 s99, s99, 64
	s_mul_i32 s99, s99, 0x1410
	s_add_u32 s34, s34, s99
	s_addc_u32 s35, s35, 0
	s_lshl_b32 s99, s14, 1
	s_add_i32 s99, s99, 1
	s_sub_i32 s99, s99, s32
	s_lshl_b32 s99, s99, 6
	v_subrev_u32_e32 v98, s98, v98
	v_subrev_u32_e32 v144, s98, v144
	v_mov_b64_e32 v[0:1], s[34:35]
	v_mad_i64_i32 v[6:7], s[16:17], v145, s29, v[0:1]
	v_and_b32_e32 v5, 56, v5
	v_lshl_add_u64 v[6:7], v[6:7], 0, s[22:23]
	v_lshlrev_b32_e32 v112, 1, v5
	v_lshl_add_u64 v[6:7], v[6:7], 0, v[112:113]
	global_load_dwordx4 v[6:9], v[6:7], off offset:1024
	v_add_u32_e32 v5, 0x100, v3
	v_and_b32_e32 v114, 63, v3
	v_ashrrev_i32_e32 v146, 3, v5
	v_mul_u32_u24_e32 v10, 0x1410, v114
	v_mov_b32_e32 v11, v113
	v_mad_i64_i32 v[0:1], s[16:17], v146, s29, v[0:1]
	v_readlane_b32 s48, v165, 26
	v_lshl_add_u64 v[10:11], s[34:35], 0, v[10:11]
	v_and_b32_e32 v100, -8, v145
	v_lshl_add_u64 v[0:1], v[0:1], 0, s[22:23]
	v_and_b32_e32 v102, -8, v146
	s_lshl_b32 s15, s18, 15
	v_readlane_b32 s62, v165, 40
	v_lshl_add_u64 v[14:15], v[10:11], 0, s[22:23]
	v_ashrrev_i32_e32 v101, 31, v100
	v_lshl_add_u64 v[0:1], v[0:1], 0, v[112:113]
	v_ashrrev_i32_e32 v103, 31, v102
	v_readlane_b32 s63, v165, 41
	s_add_u32 s16, s62, s15
	v_lshl_add_u64 v[16:17], v[100:101], 1, v[14:15]
	global_load_dwordx4 v[10:13], v[0:1], off offset:1024
	v_lshl_add_u64 v[0:1], v[102:103], 1, v[14:15]
	s_addc_u32 s17, s63, 0
	s_lshl_b32 s98, s98, 2
	s_add_u32 s16, s16, s98
	s_addc_u32 s17, s17, 0
	v_lshlrev_b32_e32 v14, 2, v114
	v_mov_b32_e32 v15, v113
	s_movk_i32 s15, 0x90
	v_lshl_add_u64 v[104:105], s[16:17], 0, v[14:15]
	v_mad_u64_u32 v[106:107], s[16:17], v145, s15, v[112:113]
	v_mul_lo_u32 v5, v100, s15
	v_lshlrev_b32_e32 v14, 1, v114
	v_or_b32_e32 v107, v5, v14
	v_mad_u64_u32 v[108:109], s[16:17], v146, s15, v[112:113]
	v_mul_lo_u32 v5, v102, s15
	s_movk_i32 s44, 0x90
	v_or_b32_e32 v109, v5, v14
	v_cmp_gt_i32_e64 s[40:41], 64, v3
	v_lshlrev_b32_e32 v147, 2, v3
	v_readlane_b32 s49, v165, 27
	v_readlane_b32 s50, v165, 28
	v_readlane_b32 s51, v165, 29
	v_readlane_b32 s52, v165, 30
	v_readlane_b32 s53, v165, 31
	v_readlane_b32 s54, v165, 32
	v_readlane_b32 s55, v165, 33
	v_readlane_b32 s56, v165, 34
	v_readlane_b32 s57, v165, 35
	v_readlane_b32 s58, v165, 36
	v_readlane_b32 s59, v165, 37
	v_readlane_b32 s60, v165, 38
	v_readlane_b32 s61, v165, 39
	s_waitcnt vmcnt(1)
	ds_write_b128 v106, v[6:9]
	global_load_dwordx4 v[6:9], v[16:17], off offset:2048
	s_waitcnt vmcnt(0)
	ds_write_b16 v107, v6 offset:9216
	ds_write_b16_d16_hi v107, v6 offset:9360
	ds_write_b16 v107, v7 offset:9504
	ds_write_b16_d16_hi v107, v7 offset:9648
	ds_write_b16 v107, v8 offset:9792
	ds_write_b16_d16_hi v107, v8 offset:9936
	ds_write_b16 v107, v9 offset:10080
	ds_write_b16_d16_hi v107, v9 offset:10224
	global_load_dwordx4 v[6:9], v[0:1], off offset:2048
	ds_write_b128 v108, v[10:13]
	s_waitcnt vmcnt(0)
	ds_write_b16 v109, v6 offset:9216
	ds_write_b16_d16_hi v109, v6 offset:9360
	ds_write_b16 v109, v7 offset:9504
	ds_write_b16_d16_hi v109, v7 offset:9648
	ds_write_b16 v109, v8 offset:9792
	ds_write_b16_d16_hi v109, v8 offset:9936
	ds_write_b16 v109, v9 offset:10080
	ds_write_b16_d16_hi v109, v9 offset:10224
	s_and_saveexec_b64 s[24:25], s[40:41]
	s_cbranch_execz .LBB0_109
	v_mov_b32_e32 v0, s99
	v_lshlrev_b32_e32 v0, 2, v0
	v_mov_b32_e32 v1, 0
	v_lshl_add_u64 v[0:1], v[104:105], 0, v[0:1]
	global_load_dword v0, v[0:1], off
	s_waitcnt vmcnt(0)
	ds_write_b32 v147, v0 offset:18432
; __device__ void attn_item(const Params& p, int s_idx, char* smem) {
;     ...
;     auto compute = [&](int kt, int buf) {
;         if (kt <= wave_last) {
;             const bf16_t* sK = (const bf16_t*)(smem + buf * ATT_BUF); const bf16_t* sVt = sK + 64 * 72; const float* sKb = (const float*)(smem + buf * ATT_BUF + 18432);
;             f32x16 S0, S1;
; #pragma unroll
;             for (int i = 0; i < 16; ++i) { S0[i] = 0.f; S1[i] = 0.f; }
; #pragma unroll
;             for (int kk = 0; kk < 4; ++kk) {
;                 const bf16x8 k0 = *(const bf16x8*)(sK + pr * 72 + kk * 16 + hh * 8);
;                 const bf16x8 k1 = *(const bf16x8*)(sK + (32 + pr) * 72 + kk * 16 + hh * 8);
;                 S0 = __builtin_amdgcn_mfma_f32_32x32x16_bf16(k0, qf[kk], S0, 0, 0, 0);
;                 S1 = __builtin_amdgcn_mfma_f32_32x32x16_bf16(k1, qf[kk], S1, 0, 0, 0);
;             }
;             float sv[32];
; #pragma unroll
;             for (int g = 0; g < 4; ++g) {
;                 const int kbase = (g >> 1) * 32 + (g & 1) * 16 + 8 * hh;
;                 const float4 b0 = *(const float4*)(sKb + kbase), b1 = *(const float4*)(sKb + kbase + 4);
;                 const int o = (g & 1) * 8;
;                 if (g >> 1) {
;                     sv[g * 8 + 0] = S1[o + 0] * sc + b0.x; sv[g * 8 + 1] = S1[o + 1] * sc + b0.y; sv[g * 8 + 2] = S1[o + 2] * sc + b0.z; sv[g * 8 + 3] = S1[o + 3] * sc + b0.w;
;                     sv[g * 8 + 4] = S1[o + 4] * sc + b1.x; sv[g * 8 + 5] = S1[o + 5] * sc + b1.y; sv[g * 8 + 6] = S1[o + 6] * sc + b1.z; sv[g * 8 + 7] = S1[o + 7] * sc + b1.w;
;                 } else {
;                     sv[g * 8 + 0] = S0[o + 0] * sc + b0.x; sv[g * 8 + 1] = S0[o + 1] * sc + b0.y; sv[g * 8 + 2] = S0[o + 2] * sc + b0.z; sv[g * 8 + 3] = S0[o + 3] * sc + b0.w;
;                     sv[g * 8 + 4] = S0[o + 4] * sc + b1.x; sv[g * 8 + 5] = S0[o + 5] * sc + b1.y; sv[g * 8 + 6] = S0[o + 6] * sc + b1.z; sv[g * 8 + 7] = S0[o + 7] * sc + b1.w;
;                 }
;             }
;     ...
;     for (int kt = 0; kt < nkt; kt += 2) {
;         gload(kt + 1, sa);
;         compute(kt, 0);
.LBB0_109:
	s_or_b64 exec, exec, s[24:25]
	v_and_b32_e32 v0, 19, v3
	v_lshlrev_b32_e32 v1, 1, v2
	v_lshrrev_b32_e32 v3, 1, v3
	v_and_b32_e32 v1, 8, v1
	v_and_b32_e32 v3, 4, v3
	v_lshlrev_b32_e32 v141, 3, v4
	s_lshl_b32 s14, s14, 1
	v_or3_b32 v0, v3, v0, v1
	s_mul_i32 s98, s99, 0x1410
	s_sub_u32 s34, s34, s98
	s_subb_u32 s35, s35, 0
	s_add_u32 s34, s34, s22
	v_mul_u32_u24_e32 v0, 0x48, v0
	v_lshlrev_b32_e32 v1, 1, v141
	v_mul_u32_u24_e32 v148, 0x48, v2
	v_mov_b32_e32 v14, v113
	v_mov_b32_e32 v15, v113
	s_addc_u32 s35, s35, 0
	v_lshl_add_u32 v150, v0, 1, v1
	v_lshl_add_u32 v152, v148, 1, v1
	s_mov_b32 s20, 0
	v_mov_b32_e32 v0, v113
	v_mov_b32_e32 v1, v113
	v_mov_b32_e32 v2, v113
	v_mov_b32_e32 v3, v113
	v_mov_b32_e32 v4, v113
	v_mov_b32_e32 v5, v113
	v_mov_b32_e32 v6, v113
	v_mov_b32_e32 v7, v113
	v_mov_b32_e32 v8, v113
	v_mov_b32_e32 v9, v113
	v_mov_b32_e32 v10, v113
	v_mov_b32_e32 v11, v113
	v_mov_b32_e32 v12, v113
	v_mov_b32_e32 v13, v113
	v_mov_b64_e32 v[30:31], v[14:15]
	v_ashrrev_i32_e32 v149, 6, v144
	v_lshl_add_u64 v[110:111], s[34:35], 0, v[112:113]
	v_lshlrev_b32_e32 v151, 2, v141
	s_or_b32 s15, s14, 1
	s_sub_i32 s14, s14, s32
	s_sub_i32 s15, s15, s32
	v_mov_b32_e32 v97, v98
	v_mov_b32_e32 v99, v98
	v_add_u32_e32 v153, 0xffffffc0, v146
	v_add_u32_e32 v154, 0xffffffc0, v114
	v_add_u32_e32 v155, 0xffffffc0, v145
	v_mov_b32_e32 v157, 0xff800000
	v_mov_b32_e32 v156, 0
	s_mov_b32 s16, s15
	s_lshl_b32 s20, s15, 6
	v_mov_b64_e32 v[28:29], v[12:13]
	v_mov_b64_e32 v[26:27], v[10:11]
	v_mov_b64_e32 v[24:25], v[8:9]
	v_mov_b64_e32 v[22:23], v[6:7]
	v_mov_b64_e32 v[20:21], v[4:5]
	v_mov_b64_e32 v[18:19], v[2:3]
	v_mov_b64_e32 v[16:17], v[0:1]
	s_waitcnt lgkmcnt(0)
	s_barrier
.LBB0_110:
	v_add_u32_e32 v32, s20, v155
	v_add_u32_e32 v36, s20, v154
	v_mov_b64_e32 v[34:35], s[34:35]
	v_mad_i64_i32 v[32:33], s[18:19], v32, s29, v[110:111]
	v_mad_u64_u32 v[34:35], s[18:19], v36, s29, v[34:35]
	v_lshl_add_u64 v[36:37], v[100:101], 1, v[34:35]
	global_load_dwordx4 v[92:95], v[32:33], off offset:1024
	global_load_dwordx4 v[84:87], v[36:37], off offset:2048
	v_add_u32_e32 v32, s20, v153
	v_mad_i64_i32 v[32:33], s[18:19], v32, s29, v[110:111]
	v_lshl_add_u64 v[34:35], v[102:103], 1, v[34:35]
	global_load_dwordx4 v[88:91], v[32:33], off offset:1024
	global_load_dwordx4 v[80:83], v[34:35], off offset:2048
	v_lshl_add_u64 v[32:33], s[20:21], 2, v[104:105]
	global_load_dword v158, v[32:33], off offset:-256
	v_cmp_le_i32_e32 vcc, s16, v149
	s_and_saveexec_b64 s[36:37], vcc
	s_cbranch_execz .LBB0_114
	ds_read_b128 v[32:35], v150 offset:4608
	ds_read_b128 v[36:39], v150
	ds_read_b128 v[116:119], v150 offset:32
	ds_read_b128 v[120:123], v150 offset:4640
	s_add_i32 s17, s20, 63
	v_cmp_gt_i32_e32 vcc, s17, v144
	s_waitcnt lgkmcnt(2)
	v_mfma_f32_32x32x16_bf16 v[48:63], v[36:39], v[64:67], 0
	v_mfma_f32_32x32x16_bf16 v[32:47], v[32:35], v[64:67], 0
	s_waitcnt lgkmcnt(1)
	v_mfma_f32_32x32x16_bf16 v[48:63], v[116:119], v[68:71], v[48:63]
	s_waitcnt lgkmcnt(0)
	v_mfma_f32_32x32x16_bf16 v[32:47], v[120:123], v[68:71], v[32:47]
	ds_read_b128 v[116:119], v150 offset:64
	ds_read_b128 v[120:123], v150 offset:4672
	s_waitcnt lgkmcnt(1)
	v_mfma_f32_32x32x16_bf16 v[48:63], v[116:119], v[72:75], v[48:63]
	s_waitcnt lgkmcnt(0)
	v_mfma_f32_32x32x16_bf16 v[32:47], v[120:123], v[72:75], v[32:47]
	ds_read_b128 v[116:119], v150 offset:96
	ds_read_b128 v[120:123], v150 offset:4704
	s_waitcnt lgkmcnt(1)
	v_mfma_f32_32x32x16_bf16 v[48:63], v[116:119], v[76:79], v[48:63]
	ds_read_b128 v[116:119], v151 offset:18432
	ds_read_b128 v[160:163], v151 offset:18448
	s_waitcnt lgkmcnt(2)
	v_mfma_f32_32x32x16_bf16 v[32:47], v[120:123], v[76:79], v[32:47]
	s_waitcnt lgkmcnt(1)
	s_nop 6
	v_fma_f32 v122, v48, s30, v116
	v_fma_f32 v123, v49, s30, v117
	v_fma_f32 v120, v50, s30, v118
	v_fma_f32 v121, v51, s30, v119
	ds_read_b128 v[48:51], v151 offset:18496
	s_waitcnt lgkmcnt(1)
	v_pk_fma_f32 v[118:119], v[52:53], s[30:31], v[160:161] op_sel_hi:[1,0,1]
	v_pk_fma_f32 v[54:55], v[54:55], s[30:31], v[162:163] op_sel_hi:[1,0,1]
	ds_read_b128 v[160:163], v151 offset:18560
	s_waitcnt lgkmcnt(1)
	v_pk_fma_f32 v[116:117], v[56:57], s[30:31], v[48:49] op_sel_hi:[1,0,1]
	v_pk_fma_f32 v[50:51], v[58:59], s[30:31], v[50:51] op_sel_hi:[1,0,1]
	ds_read_b128 v[56:59], v151 offset:18512
	s_waitcnt lgkmcnt(1)
	v_pk_fma_f32 v[52:53], v[34:35], s[30:31], v[162:163] op_sel_hi:[1,0,1]
	s_waitcnt lgkmcnt(0)
	v_pk_fma_f32 v[124:125], v[60:61], s[30:31], v[56:57] op_sel_hi:[1,0,1]
	v_pk_fma_f32 v[60:61], v[62:63], s[30:31], v[58:59] op_sel_hi:[1,0,1]
	v_pk_fma_f32 v[58:59], v[32:33], s[30:31], v[160:161] op_sel_hi:[1,0,1]
	ds_read_b128 v[32:35], v151 offset:18576
	s_waitcnt lgkmcnt(0)
	v_pk_fma_f32 v[56:57], v[36:37], s[30:31], v[32:33] op_sel_hi:[1,0,1]
	v_pk_fma_f32 v[48:49], v[38:39], s[30:31], v[34:35] op_sel_hi:[1,0,1]
	ds_read_b128 v[32:35], v151 offset:18624
	s_waitcnt lgkmcnt(0)
	v_pk_fma_f32 v[38:39], v[40:41], s[30:31], v[32:33] op_sel_hi:[1,0,1]
	v_pk_fma_f32 v[34:35], v[42:43], s[30:31], v[34:35] op_sel_hi:[1,0,1]
	ds_read_b128 v[40:43], v151 offset:18640
	s_waitcnt lgkmcnt(0)
	v_pk_fma_f32 v[36:37], v[44:45], s[30:31], v[40:41] op_sel_hi:[1,0,1]
	v_pk_fma_f32 v[32:33], v[46:47], s[30:31], v[42:43] op_sel_hi:[1,0,1]
	s_and_saveexec_b64 s[42:43], vcc
	s_cbranch_execz .LBB0_113
; __device__ void attn_item(const Params& p, int s_idx, char* smem) {
;     ...
;             if (kt * 64 + 63 > wave_q0) {
; #pragma unroll
;                 for (int g = 0; g < 4; ++g) {
;                     const int kbase = kt * 64 + (g >> 1) * 32 + (g & 1) * 16 + 8 * hh;
; #pragma unroll
;                     for (int e = 0; e < 8; ++e) if (kbase + e > qrow) sv[g * 8 + e] = -INFINITY;
;                 }
;             }
	v_add_u32_e32 v40, s20, v141
	v_cmp_ge_i32_e32 vcc, v99, v40
	v_or_b32_e32 v41, 3, v40
	v_or_b32_e32 v42, 2, v40
	v_cndmask_b32_e32 v122, v139, v122, vcc
	v_cmp_lt_i32_e32 vcc, v40, v99
	s_nop 1
	v_cndmask_b32_e32 v123, v139, v123, vcc
	v_cmp_le_i32_e32 vcc, v41, v97
	v_or_b32_e32 v41, 5, v40
	s_nop 0
	v_cndmask_b32_e32 v121, v139, v121, vcc
	v_cmp_le_i32_e32 vcc, v42, v98
	v_or_b32_e32 v42, 4, v40
	s_nop 0
	v_cndmask_b32_e32 v120, v139, v120, vcc
	v_cmp_le_i32_e32 vcc, v41, v97
	v_or_b32_e32 v41, 7, v40
	s_nop 0
	v_cndmask_b32_e32 v119, v139, v119, vcc
	v_cmp_le_i32_e32 vcc, v42, v98
	v_or_b32_e32 v42, 6, v40
	s_nop 0
	v_cndmask_b32_e32 v118, v139, v118, vcc
	v_cmp_le_i32_e32 vcc, v41, v97
	v_or_b32_e32 v41, 17, v40
	s_nop 0
	v_cndmask_b32_e32 v55, v139, v55, vcc
	v_cmp_le_i32_e32 vcc, v42, v98
	v_or_b32_e32 v42, 16, v40
	s_nop 0
	v_cndmask_b32_e32 v54, v139, v54, vcc
	v_cmp_le_i32_e32 vcc, v41, v97
	v_or_b32_e32 v41, 19, v40
	s_nop 0
	v_cndmask_b32_e32 v117, v139, v117, vcc
	v_cmp_le_i32_e32 vcc, v42, v98
	v_or_b32_e32 v42, 18, v40
	s_nop 0
	v_cndmask_b32_e32 v116, v139, v116, vcc
	v_cmp_le_i32_e32 vcc, v41, v97
	v_or_b32_e32 v41, 21, v40
	s_nop 0
	v_cndmask_b32_e32 v51, v139, v51, vcc
	v_cmp_le_i32_e32 vcc, v42, v98
	v_or_b32_e32 v42, 20, v40
	s_nop 0
	v_cndmask_b32_e32 v50, v139, v50, vcc
	v_cmp_le_i32_e32 vcc, v41, v97
	v_or_b32_e32 v41, 23, v40
	s_nop 0
	v_cndmask_b32_e32 v125, v139, v125, vcc
	v_cmp_le_i32_e32 vcc, v42, v98
	v_or_b32_e32 v42, 22, v40
	s_nop 0
	v_cndmask_b32_e32 v124, v139, v124, vcc
	v_cmp_le_i32_e32 vcc, v41, v97
	v_or_b32_e32 v41, 33, v40
	s_nop 0
	v_cndmask_b32_e32 v61, v139, v61, vcc
	v_cmp_le_i32_e32 vcc, v42, v98
	v_or_b32_e32 v42, 32, v40
	s_nop 0
	v_cndmask_b32_e32 v60, v139, v60, vcc
	v_cmp_le_i32_e32 vcc, v41, v97
	v_or_b32_e32 v41, 35, v40
	s_nop 0
	v_cndmask_b32_e32 v59, v139, v59, vcc
	v_cmp_le_i32_e32 vcc, v42, v98
	v_or_b32_e32 v42, 34, v40
	s_nop 0
	v_cndmask_b32_e32 v58, v139, v58, vcc
	v_cmp_le_i32_e32 vcc, v41, v97
	v_or_b32_e32 v41, 37, v40
	s_nop 0
	v_cndmask_b32_e32 v53, v139, v53, vcc
	v_cmp_le_i32_e32 vcc, v42, v98
	v_or_b32_e32 v42, 36, v40
	s_nop 0
	v_cndmask_b32_e32 v52, v139, v52, vcc
	v_cmp_le_i32_e32 vcc, v41, v97
	v_or_b32_e32 v41, 39, v40
	s_nop 0
	v_cndmask_b32_e32 v57, v139, v57, vcc
	v_cmp_le_i32_e32 vcc, v42, v98
	v_or_b32_e32 v42, 38, v40
	s_nop 0
	v_cndmask_b32_e32 v56, v139, v56, vcc
	v_cmp_le_i32_e32 vcc, v41, v97
	v_or_b32_e32 v41, 49, v40
	s_nop 0
	v_cndmask_b32_e32 v49, v139, v49, vcc
	v_cmp_le_i32_e32 vcc, v42, v98
	v_or_b32_e32 v42, 48, v40
	s_nop 0
	v_cndmask_b32_e32 v48, v139, v48, vcc
	v_cmp_le_i32_e32 vcc, v41, v97
	v_or_b32_e32 v41, 51, v40
	s_nop 0
	v_cndmask_b32_e32 v39, v139, v39, vcc
	v_cmp_le_i32_e32 vcc, v42, v98
	v_or_b32_e32 v42, 50, v40
	s_nop 0
	v_cndmask_b32_e32 v38, v139, v38, vcc
	v_cmp_le_i32_e32 vcc, v41, v97
	v_or_b32_e32 v41, 53, v40
	s_nop 0
	v_cndmask_b32_e32 v35, v139, v35, vcc
	v_cmp_le_i32_e32 vcc, v42, v98
	v_or_b32_e32 v42, 52, v40
	s_nop 0
	v_cndmask_b32_e32 v34, v139, v34, vcc
	v_cmp_le_i32_e32 vcc, v41, v97
	v_or_b32_e32 v41, 55, v40
	v_or_b32_e32 v40, 54, v40
	v_cndmask_b32_e32 v37, v139, v37, vcc
	v_cmp_le_i32_e32 vcc, v42, v98
	s_nop 1
	v_cndmask_b32_e32 v36, v139, v36, vcc
	v_cmp_le_i32_e32 vcc, v41, v97
	s_nop 1
	v_cndmask_b32_e32 v33, v139, v33, vcc
	v_cmp_le_i32_e32 vcc, v40, v98
	s_nop 1
	v_cndmask_b32_e32 v32, v139, v32, vcc
; __device__ __forceinline__ unsigned pk_bf16(float lo, float hi) { unsigned r; asm("v_cvt_pk_bf16_f32 %0, %1, %2" : "=v"(r) : "v"(lo), "v"(hi)); return r; }
; __device__ void attn_item(const Params& p, int s_idx, char* smem) {
;     ...
;             float mx = sv[0];
; #pragma unroll
;             for (int i = 1; i < 32; ++i) mx = fmaxf(mx, sv[i]);
;             mx = fmaxf(mx, __shfl_xor(mx, 32));
;             const float mnew = fmaxf(mrun, mx);
;             const float alpha = __builtin_amdgcn_exp2f(mrun - mnew);
;             mrun = mnew;
;             float psum = 0.f;
; #pragma unroll
;             for (int i = 0; i < 32; ++i) { sv[i] = __builtin_amdgcn_exp2f(sv[i] - mnew); psum += sv[i]; }
;             lsum = lsum * alpha + psum;
; #pragma unroll
;             for (int i = 0; i < 16; ++i) { O0[i] *= alpha; O1[i] *= alpha; }
; #pragma unroll
;             for (int g = 0; g < 4; ++g) {
;                 bf16x8 pf;
;                 {
;                     const unsigned u0 = pk_bf16(sv[g * 8 + 0], sv[g * 8 + 1]), u1 = pk_bf16(sv[g * 8 + 2], sv[g * 8 + 3]);
;                     const unsigned u2 = pk_bf16(sv[g * 8 + 4], sv[g * 8 + 5]), u3 = pk_bf16(sv[g * 8 + 6], sv[g * 8 + 7]);
;                     const uint4 uu = {u0, u1, u2, u3};
;                     pf = __builtin_bit_cast(bf16x8, uu);
;                 }
;                 const int koff = (g >> 1) * 32 + (g & 1) * 16 + 8 * hh;
;                 const bf16x8 v0 = *(const bf16x8*)(sVt + ql * 72 + koff);
;                 const bf16x8 v1 = *(const bf16x8*)(sVt + (32 + ql) * 72 + koff);
;                 O0 = __builtin_amdgcn_mfma_f32_32x32x16_bf16(v0, pf, O0, 0, 0, 0);
;                 O1 = __builtin_amdgcn_mfma_f32_32x32x16_bf16(v1, pf, O1, 0, 0, 0);
;             }
.LBB0_113:
	s_or_b64 exec, exec, s[42:43]
	v_max_f32_e32 v40, v123, v123
	v_max_f32_e32 v41, v122, v122
	v_max_f32_e32 v40, v41, v40
	v_max3_f32 v40, v40, v120, v121
	v_max3_f32 v40, v40, v118, v119
	v_max3_f32 v40, v40, v54, v55
	v_max3_f32 v40, v40, v116, v117
	v_max3_f32 v40, v40, v50, v51
	v_max3_f32 v40, v40, v124, v125
	v_max3_f32 v40, v40, v60, v61
	v_max3_f32 v40, v40, v58, v59
	v_max3_f32 v40, v40, v52, v53
	v_max3_f32 v40, v40, v56, v57
	v_max3_f32 v40, v40, v48, v49
	v_max3_f32 v40, v40, v38, v39
	v_max3_f32 v40, v40, v34, v35
	v_cmp_lt_i32_e32 vcc, v133, v132
	v_max3_f32 v40, v40, v36, v37
	v_max3_f32 v40, v40, v32, v33
	v_cndmask_b32_e32 v41, v130, v133, vcc
	v_lshlrev_b32_e32 v41, 2, v41
	ds_bpermute_b32 v41, v41, v40
	s_waitcnt lgkmcnt(0)
	v_max_f32_e32 v42, v40, v41
	v_add_f32_e32 v43, 0xc3190000, v157
	v_cmp_lt_f32_e32 vcc, v42, v43
	s_andn2_b64 s[98:99], exec, vcc
	s_cbranch_scc0 .LBB0_114
	v_cmp_gt_f32_e32 vcc, v42, v157
	s_and_b64 s[98:99], exec, vcc
	v_max3_f32 v41, v157, v40, v41
	v_sub_f32_e32 v40, v122, v41
	v_exp_f32_e32 v62, v40
	v_sub_f32_e32 v40, v123, v41
	v_exp_f32_e32 v63, v40
	v_sub_f32_e32 v43, v120, v41
	v_exp_f32_e32 v120, v43
	v_sub_f32_e32 v43, v121, v41
	v_exp_f32_e32 v121, v43
	v_sub_f32_e32 v43, v118, v41
	v_add_f32_e32 v42, 0, v62
	v_exp_f32_e32 v118, v43
	v_sub_f32_e32 v43, v119, v41
	v_add_f32_e32 v42, v63, v42
	v_exp_f32_e32 v119, v43
	v_sub_f32_e32 v43, v54, v41
	v_add_f32_e32 v42, v120, v42
	v_exp_f32_e32 v122, v43
	v_sub_f32_e32 v43, v55, v41
	v_add_f32_e32 v42, v121, v42
	v_exp_f32_e32 v55, v43
	v_sub_f32_e32 v43, v116, v41
	v_add_f32_e32 v42, v118, v42
	v_exp_f32_e32 v116, v43
	v_sub_f32_e32 v43, v117, v41
	v_add_f32_e32 v42, v119, v42
	v_exp_f32_e32 v117, v43
	v_sub_f32_e32 v43, v50, v41
	v_add_f32_e32 v42, v122, v42
	v_exp_f32_e32 v123, v43
	v_sub_f32_e32 v43, v51, v41
	v_sub_f32_e32 v40, v157, v41
	v_add_f32_e32 v42, v55, v42
	v_exp_f32_e32 v157, v43
	v_sub_f32_e32 v43, v124, v41
	v_add_f32_e32 v42, v116, v42
	v_exp_f32_e32 v124, v43
	v_sub_f32_e32 v43, v125, v41
	v_add_f32_e32 v42, v117, v42
	v_exp_f32_e32 v125, v43
	v_add_f32_e32 v42, v123, v42
	v_add_f32_e32 v42, v157, v42
	v_add_f32_e32 v42, v124, v42
	v_add_f32_e32 v44, v125, v42
	v_sub_f32_e32 v42, v60, v41
	v_exp_f32_e32 v60, v42
	v_sub_f32_e32 v42, v61, v41
	v_exp_f32_e32 v61, v42
	v_sub_f32_e32 v42, v58, v41
	v_exp_f32_e32 v42, v42
	v_sub_f32_e32 v43, v59, v41
	v_exp_f32_e32 v43, v43
	v_add_f32_e32 v44, v60, v44
	v_add_f32_e32 v44, v61, v44
	v_add_f32_e32 v44, v42, v44
	v_add_f32_e32 v50, v43, v44
	v_sub_f32_e32 v44, v52, v41
	v_exp_f32_e32 v44, v44
	v_sub_f32_e32 v45, v53, v41
	v_exp_f32_e32 v45, v45
	v_sub_f32_e32 v46, v56, v41
	v_exp_f32_e32 v46, v46
	v_sub_f32_e32 v47, v57, v41
	v_exp_f32_e32 v47, v47
	v_add_f32_e32 v50, v44, v50
	v_add_f32_e32 v50, v45, v50
	v_sub_f32_e32 v48, v48, v41
	v_add_f32_e32 v50, v46, v50
	v_exp_f32_e32 v160, v48
	v_sub_f32_e32 v48, v49, v41
	v_add_f32_e32 v159, v47, v50
	v_exp_f32_e32 v161, v48
	ds_read_b128 v[48:51], v152 offset:9216
	ds_read_b128 v[56:59], v152 offset:13824
	v_exp_f32_e32 v40, v40
	v_cvt_pk_bf16_f32 v52, v62, v63
	v_cvt_pk_bf16_f32 v53, v120, v121
	v_cvt_pk_bf16_f32 v54, v118, v119
	v_cvt_pk_bf16_f32 v55, v122, v55
	v_sub_f32_e32 v38, v38, v41
	s_cmp_eq_u64 s[98:99], 0
	s_cbranch_scc1 .Lnr1a
	v_pk_mul_f32 v[14:15], v[14:15], v[40:41] op_sel_hi:[1,0]
	v_pk_mul_f32 v[12:13], v[12:13], v[40:41] op_sel_hi:[1,0]
	v_pk_mul_f32 v[10:11], v[10:11], v[40:41] op_sel_hi:[1,0]
	v_pk_mul_f32 v[8:9], v[8:9], v[40:41] op_sel_hi:[1,0]
	v_pk_mul_f32 v[6:7], v[6:7], v[40:41] op_sel_hi:[1,0]
	v_pk_mul_f32 v[4:5], v[4:5], v[40:41] op_sel_hi:[1,0]
	v_pk_mul_f32 v[2:3], v[2:3], v[40:41] op_sel_hi:[1,0]
	v_pk_mul_f32 v[0:1], v[0:1], v[40:41] op_sel_hi:[1,0]
	v_pk_mul_f32 v[30:31], v[30:31], v[40:41] op_sel_hi:[1,0]
	v_pk_mul_f32 v[28:29], v[28:29], v[40:41] op_sel_hi:[1,0]
.Lnr1a:
	s_waitcnt lgkmcnt(1)
	v_mfma_f32_32x32x16_bf16 v[0:15], v[48:51], v[52:55], v[0:15]
	ds_read_b128 v[48:51], v152 offset:9248
	s_cmp_eq_u64 s[98:99], 0
	s_cbranch_scc1 .Lnr2a
	v_mul_f32_e64 v26, v26, v40
	v_mul_f32_e64 v27, v27, v40
	v_mul_f32_e64 v24, v24, v40
	v_mul_f32_e64 v25, v25, v40
	v_pk_mul_f32 v[22:23], v[22:23], v[40:41] op_sel_hi:[1,0]
	v_pk_mul_f32 v[20:21], v[20:21], v[40:41] op_sel_hi:[1,0]
	v_pk_mul_f32 v[18:19], v[18:19], v[40:41] op_sel_hi:[1,0]
	v_pk_mul_f32 v[16:17], v[16:17], v[40:41] op_sel_hi:[1,0]
.Lnr2a:
	v_exp_f32_e32 v38, v38
	v_sub_f32_e32 v39, v39, v41
	s_waitcnt lgkmcnt(1)
	v_mfma_f32_32x32x16_bf16 v[16:31], v[56:59], v[52:55], v[16:31]
	ds_read_b128 v[56:59], v152 offset:13856
	v_exp_f32_e32 v39, v39
	v_cvt_pk_bf16_f32 v52, v116, v117
	v_cvt_pk_bf16_f32 v53, v123, v157
	v_cvt_pk_bf16_f32 v54, v124, v125
	v_cvt_pk_bf16_f32 v55, v60, v61
	v_sub_f32_e32 v34, v34, v41
	s_waitcnt lgkmcnt(1)
	v_mfma_f32_32x32x16_bf16 v[0:15], v[48:51], v[52:55], v[0:15]
	v_add_f32_e32 v48, v160, v159
	v_add_f32_e32 v48, v161, v48
	v_add_f32_e32 v48, v38, v48
	v_add_f32_e32 v60, v39, v48
	ds_read_b128 v[48:51], v152 offset:9280
	v_exp_f32_e32 v61, v34
	v_sub_f32_e32 v34, v35, v41
	s_waitcnt lgkmcnt(1)
	v_mfma_f32_32x32x16_bf16 v[16:31], v[56:59], v[52:55], v[16:31]
	ds_read_b128 v[52:55], v152 offset:13888
	v_exp_f32_e32 v56, v34
	v_sub_f32_e32 v34, v36, v41
	v_cvt_pk_bf16_f32 v42, v42, v43
	v_cvt_pk_bf16_f32 v43, v44, v45
	v_cvt_pk_bf16_f32 v44, v46, v47
	v_cvt_pk_bf16_f32 v45, v160, v161
	v_sub_f32_e32 v32, v32, v41
	s_waitcnt lgkmcnt(1)
	v_mfma_f32_32x32x16_bf16 v[0:15], v[48:51], v[42:45], v[0:15]
	v_exp_f32_e32 v50, v34
	v_sub_f32_e32 v34, v37, v41
	v_exp_f32_e32 v51, v34
	ds_read_b128 v[34:37], v152 offset:9312
	ds_read_b128 v[46:49], v152 offset:13920
	v_sub_f32_e32 v33, v33, v41
	v_exp_f32_e32 v32, v32
	s_waitcnt lgkmcnt(2)
	v_mfma_f32_32x32x16_bf16 v[16:31], v[52:55], v[42:45], v[16:31]
	v_exp_f32_e32 v33, v33
	v_cvt_pk_bf16_f32 v42, v38, v39
	v_cvt_pk_bf16_f32 v43, v61, v56
	v_cvt_pk_bf16_f32 v44, v50, v51
	v_cvt_pk_bf16_f32 v45, v32, v33
	v_mov_b32_e32 v157, v41
	s_waitcnt lgkmcnt(1)
	v_mfma_f32_32x32x16_bf16 v[0:15], v[34:37], v[42:45], v[0:15]
	v_add_f32_e32 v34, v61, v60
	v_add_f32_e32 v34, v56, v34
	v_add_f32_e32 v34, v50, v34
	v_add_f32_e32 v34, v51, v34
	v_add_f32_e32 v32, v32, v34
	v_add_f32_e32 v32, v33, v32
	v_fmac_f32_e32 v32, v156, v40
	s_waitcnt lgkmcnt(0)
	v_mfma_f32_32x32x16_bf16 v[16:31], v[46:49], v[42:45], v[16:31]
	v_mov_b32_e32 v156, v32

; __device__ void attn_item(const Params& p, int s_idx, char* smem) {
;     ...
;             if (kt * 64 + 63 > wave_q0) {
; #pragma unroll
;                 for (int g = 0; g < 4; ++g) {
;                     const int kbase = kt * 64 + (g >> 1) * 32 + (g & 1) * 16 + 8 * hh;
; #pragma unroll
;                     for (int e = 0; e < 8; ++e) if (kbase + e > qrow) sv[g * 8 + e] = -INFINITY;
;                 }
;             }
;     ...
;         gload(kt + 1, sa);
;         compute(kt, 0);
;         sstore(1, sa);
;         __syncthreads();
;         gload(min(kt + 2, nkt - 1), sa);
;         compute(kt + 1, 1);
.LBB0_116:
	s_or_b64 exec, exec, s[24:25]
	s_add_i32 s17, s16, -2
	s_max_i32 s18, s17, 0
	s_lshl_b32 s18, s18, 6
	v_add_u32_e32 v32, s18, v145
	v_or_b32_e32 v36, s18, v114
	v_mov_b64_e32 v[34:35], s[34:35]
	v_mad_i64_i32 v[32:33], s[24:25], v32, s29, v[110:111]
	v_mad_u64_u32 v[34:35], s[24:25], v36, s29, v[34:35]
	s_waitcnt lgkmcnt(0)
	s_barrier
	v_lshl_add_u64 v[36:37], v[100:101], 1, v[34:35]
	global_load_dwordx4 v[92:95], v[32:33], off offset:1024
	global_load_dwordx4 v[84:87], v[36:37], off offset:2048
	v_add_u32_e32 v32, s18, v146
	v_mad_i64_i32 v[32:33], s[24:25], v32, s29, v[110:111]
	s_mov_b32 s19, s21
	v_lshl_add_u64 v[34:35], v[102:103], 1, v[34:35]
	global_load_dwordx4 v[88:91], v[32:33], off offset:1024
	global_load_dwordx4 v[80:83], v[34:35], off offset:2048
	v_lshl_add_u64 v[32:33], s[18:19], 2, v[104:105]
	global_load_dword v158, v[32:33], off
	v_cmp_lt_i32_e32 vcc, s17, v149
	s_and_saveexec_b64 s[36:37], vcc
	s_cbranch_execz .LBB0_120
	ds_read_b128 v[32:35], v150 offset:23296
	ds_read_b128 v[36:39], v150 offset:18688
	ds_read_b128 v[116:119], v150 offset:18720
	ds_read_b128 v[120:123], v150 offset:23328
	s_add_i32 s18, s20, -1
	v_cmp_gt_i32_e32 vcc, s18, v144
	s_waitcnt lgkmcnt(2)
	v_mfma_f32_32x32x16_bf16 v[48:63], v[36:39], v[64:67], 0
	v_mfma_f32_32x32x16_bf16 v[32:47], v[32:35], v[64:67], 0
	s_waitcnt lgkmcnt(1)
	v_mfma_f32_32x32x16_bf16 v[48:63], v[116:119], v[68:71], v[48:63]
	s_waitcnt lgkmcnt(0)
	v_mfma_f32_32x32x16_bf16 v[32:47], v[120:123], v[68:71], v[32:47]
	ds_read_b128 v[116:119], v150 offset:18752
	ds_read_b128 v[120:123], v150 offset:23360
	s_waitcnt lgkmcnt(1)
	v_mfma_f32_32x32x16_bf16 v[48:63], v[116:119], v[72:75], v[48:63]
	s_waitcnt lgkmcnt(0)
	v_mfma_f32_32x32x16_bf16 v[32:47], v[120:123], v[72:75], v[32:47]
	ds_read_b128 v[116:119], v150 offset:18784
	ds_read_b128 v[120:123], v150 offset:23392
	s_waitcnt lgkmcnt(1)
	v_mfma_f32_32x32x16_bf16 v[48:63], v[116:119], v[76:79], v[48:63]
	ds_read_b128 v[116:119], v151 offset:37120
	ds_read_b128 v[160:163], v151 offset:37136
	s_waitcnt lgkmcnt(2)
	v_mfma_f32_32x32x16_bf16 v[32:47], v[120:123], v[76:79], v[32:47]
	s_waitcnt lgkmcnt(1)
	s_nop 6
	v_fma_f32 v122, v48, s30, v116
	v_fma_f32 v123, v49, s30, v117
	v_fma_f32 v120, v50, s30, v118
	v_fma_f32 v121, v51, s30, v119
	ds_read_b128 v[48:51], v151 offset:37184
	s_waitcnt lgkmcnt(1)
	v_pk_fma_f32 v[118:119], v[52:53], s[30:31], v[160:161] op_sel_hi:[1,0,1]
	v_pk_fma_f32 v[54:55], v[54:55], s[30:31], v[162:163] op_sel_hi:[1,0,1]
	ds_read_b128 v[160:163], v151 offset:37248
	s_waitcnt lgkmcnt(1)
	v_pk_fma_f32 v[116:117], v[56:57], s[30:31], v[48:49] op_sel_hi:[1,0,1]
	v_pk_fma_f32 v[50:51], v[58:59], s[30:31], v[50:51] op_sel_hi:[1,0,1]
	ds_read_b128 v[56:59], v151 offset:37200
	s_waitcnt lgkmcnt(1)
	v_pk_fma_f32 v[52:53], v[34:35], s[30:31], v[162:163] op_sel_hi:[1,0,1]
	s_waitcnt lgkmcnt(0)
	v_pk_fma_f32 v[124:125], v[60:61], s[30:31], v[56:57] op_sel_hi:[1,0,1]
	v_pk_fma_f32 v[60:61], v[62:63], s[30:31], v[58:59] op_sel_hi:[1,0,1]
	v_pk_fma_f32 v[58:59], v[32:33], s[30:31], v[160:161] op_sel_hi:[1,0,1]
	ds_read_b128 v[32:35], v151 offset:37264
	s_waitcnt lgkmcnt(0)
	v_pk_fma_f32 v[56:57], v[36:37], s[30:31], v[32:33] op_sel_hi:[1,0,1]
	v_pk_fma_f32 v[48:49], v[38:39], s[30:31], v[34:35] op_sel_hi:[1,0,1]
	ds_read_b128 v[32:35], v151 offset:37312
	s_waitcnt lgkmcnt(0)
	v_pk_fma_f32 v[38:39], v[40:41], s[30:31], v[32:33] op_sel_hi:[1,0,1]
	v_pk_fma_f32 v[34:35], v[42:43], s[30:31], v[34:35] op_sel_hi:[1,0,1]
	ds_read_b128 v[40:43], v151 offset:37328
	s_waitcnt lgkmcnt(0)
	v_pk_fma_f32 v[36:37], v[44:45], s[30:31], v[40:41] op_sel_hi:[1,0,1]
	v_pk_fma_f32 v[32:33], v[46:47], s[30:31], v[42:43] op_sel_hi:[1,0,1]
	s_and_saveexec_b64 s[42:43], vcc
	s_cbranch_execz .LBB0_119
	s_add_i32 s19, s20, 0xffffffc0
	v_add_u32_e32 v40, s19, v141
	v_cmp_ge_i32_e32 vcc, v99, v40
	v_or_b32_e32 v41, 3, v40
	v_or_b32_e32 v42, 2, v40
	v_cndmask_b32_e32 v122, v139, v122, vcc
	v_cmp_lt_i32_e32 vcc, v40, v99
	s_nop 1
	v_cndmask_b32_e32 v123, v139, v123, vcc
	v_cmp_le_i32_e32 vcc, v41, v97
	v_or_b32_e32 v41, 5, v40
	s_nop 0
	v_cndmask_b32_e32 v121, v139, v121, vcc
	v_cmp_le_i32_e32 vcc, v42, v98
	v_or_b32_e32 v42, 4, v40
	s_nop 0
	v_cndmask_b32_e32 v120, v139, v120, vcc
	v_cmp_le_i32_e32 vcc, v41, v97
	v_or_b32_e32 v41, 7, v40
	s_nop 0
	v_cndmask_b32_e32 v119, v139, v119, vcc
	v_cmp_le_i32_e32 vcc, v42, v98
	v_or_b32_e32 v42, 6, v40
	s_nop 0
	v_cndmask_b32_e32 v118, v139, v118, vcc
	v_cmp_le_i32_e32 vcc, v41, v97
	v_or_b32_e32 v41, 17, v40
	s_nop 0
	v_cndmask_b32_e32 v55, v139, v55, vcc
	v_cmp_le_i32_e32 vcc, v42, v98
	v_or_b32_e32 v42, 16, v40
	s_nop 0
	v_cndmask_b32_e32 v54, v139, v54, vcc
	v_cmp_le_i32_e32 vcc, v41, v97
	v_or_b32_e32 v41, 19, v40
	s_nop 0
	v_cndmask_b32_e32 v117, v139, v117, vcc
	v_cmp_le_i32_e32 vcc, v42, v98
	v_or_b32_e32 v42, 18, v40
	s_nop 0
	v_cndmask_b32_e32 v116, v139, v116, vcc
	v_cmp_le_i32_e32 vcc, v41, v97
	v_or_b32_e32 v41, 21, v40
	s_nop 0
	v_cndmask_b32_e32 v51, v139, v51, vcc
	v_cmp_le_i32_e32 vcc, v42, v98
	v_or_b32_e32 v42, 20, v40
	s_nop 0
	v_cndmask_b32_e32 v50, v139, v50, vcc
	v_cmp_le_i32_e32 vcc, v41, v97
	v_or_b32_e32 v41, 23, v40
	s_nop 0
	v_cndmask_b32_e32 v125, v139, v125, vcc
	v_cmp_le_i32_e32 vcc, v42, v98
	v_or_b32_e32 v42, 22, v40
	s_nop 0
	v_cndmask_b32_e32 v124, v139, v124, vcc
	v_cmp_le_i32_e32 vcc, v41, v97
	v_or_b32_e32 v41, 33, v40
	s_nop 0
	v_cndmask_b32_e32 v61, v139, v61, vcc
	v_cmp_le_i32_e32 vcc, v42, v98
	v_or_b32_e32 v42, 32, v40
	s_nop 0
	v_cndmask_b32_e32 v60, v139, v60, vcc
	v_cmp_le_i32_e32 vcc, v41, v97
	v_or_b32_e32 v41, 35, v40
	s_nop 0
	v_cndmask_b32_e32 v59, v139, v59, vcc
; __device__ void attn_item(const Params& p, int s_idx, char* smem) {
;     ...
;             if (kt * 64 + 63 > wave_q0) {
; #pragma unroll
;                 for (int g = 0; g < 4; ++g) {
;                     const int kbase = kt * 64 + (g >> 1) * 32 + (g & 1) * 16 + 8 * hh;
; #pragma unroll
;                     for (int e = 0; e < 8; ++e) if (kbase + e > qrow) sv[g * 8 + e] = -INFINITY;
;                 }
;             }
;             float mx = sv[0];
; #pragma unroll
;             for (int i = 1; i < 32; ++i) mx = fmaxf(mx, sv[i]);
;             mx = fmaxf(mx, __shfl_xor(mx, 32));
;             const float mnew = fmaxf(mrun, mx);
;             const float alpha = __builtin_amdgcn_exp2f(mrun - mnew);
;             mrun = mnew;
;             float psum = 0.f;
; #pragma unroll
;             for (int i = 0; i < 32; ++i) { sv[i] = __builtin_amdgcn_exp2f(sv[i] - mnew); psum += sv[i]; }
;             lsum = lsum * alpha + psum;
; #pragma unroll
;             for (int i = 0; i < 16; ++i) { O0[i] *= alpha; O1[i] *= alpha; }
	v_cmp_le_i32_e32 vcc, v42, v98
	v_or_b32_e32 v42, 34, v40
	s_nop 0
	v_cndmask_b32_e32 v58, v139, v58, vcc
	v_cmp_le_i32_e32 vcc, v41, v97
	v_or_b32_e32 v41, 37, v40
	s_nop 0
	v_cndmask_b32_e32 v53, v139, v53, vcc
	v_cmp_le_i32_e32 vcc, v42, v98
	v_or_b32_e32 v42, 36, v40
	s_nop 0
	v_cndmask_b32_e32 v52, v139, v52, vcc
	v_cmp_le_i32_e32 vcc, v41, v97
	v_or_b32_e32 v41, 39, v40
	s_nop 0
	v_cndmask_b32_e32 v57, v139, v57, vcc
	v_cmp_le_i32_e32 vcc, v42, v98
	v_or_b32_e32 v42, 38, v40
	s_nop 0
	v_cndmask_b32_e32 v56, v139, v56, vcc
	v_cmp_le_i32_e32 vcc, v41, v97
	v_or_b32_e32 v41, 49, v40
	s_nop 0
	v_cndmask_b32_e32 v49, v139, v49, vcc
	v_cmp_le_i32_e32 vcc, v42, v98
	v_or_b32_e32 v42, 48, v40
	s_nop 0
	v_cndmask_b32_e32 v48, v139, v48, vcc
	v_cmp_le_i32_e32 vcc, v41, v97
	v_or_b32_e32 v41, 51, v40
	s_nop 0
	v_cndmask_b32_e32 v39, v139, v39, vcc
	v_cmp_le_i32_e32 vcc, v42, v98
	v_or_b32_e32 v42, 50, v40
	s_nop 0
	v_cndmask_b32_e32 v38, v139, v38, vcc
	v_cmp_le_i32_e32 vcc, v41, v97
	v_or_b32_e32 v41, 53, v40
	s_nop 0
	v_cndmask_b32_e32 v35, v139, v35, vcc
	v_cmp_le_i32_e32 vcc, v42, v98
	v_or_b32_e32 v42, 52, v40
	s_nop 0
	v_cndmask_b32_e32 v34, v139, v34, vcc
	v_cmp_le_i32_e32 vcc, v41, v97
	v_or_b32_e32 v41, 55, v40
	v_or_b32_e32 v40, 54, v40
	v_cndmask_b32_e32 v37, v139, v37, vcc
	v_cmp_le_i32_e32 vcc, v42, v98
	s_nop 1
	v_cndmask_b32_e32 v36, v139, v36, vcc
	v_cmp_le_i32_e32 vcc, v41, v97
	s_nop 1
	v_cndmask_b32_e32 v33, v139, v33, vcc
	v_cmp_le_i32_e32 vcc, v40, v98
	s_nop 1
	v_cndmask_b32_e32 v32, v139, v32, vcc
.LBB0_119:
	s_or_b64 exec, exec, s[42:43]
	v_max_f32_e32 v40, v123, v123
	v_max_f32_e32 v41, v122, v122
	v_max_f32_e32 v40, v41, v40
	v_max3_f32 v40, v40, v120, v121
	v_max3_f32 v40, v40, v118, v119
	v_max3_f32 v40, v40, v54, v55
	v_max3_f32 v40, v40, v116, v117
	v_max3_f32 v40, v40, v50, v51
	v_max3_f32 v40, v40, v124, v125
	v_max3_f32 v40, v40, v60, v61
	v_max3_f32 v40, v40, v58, v59
	v_max3_f32 v40, v40, v52, v53
	v_max3_f32 v40, v40, v56, v57
	v_max3_f32 v40, v40, v48, v49
	v_max3_f32 v40, v40, v38, v39
	v_max3_f32 v40, v40, v34, v35
	v_cmp_lt_i32_e32 vcc, v133, v132
	v_max3_f32 v40, v40, v36, v37
	v_max3_f32 v40, v40, v32, v33
	v_cndmask_b32_e32 v41, v130, v133, vcc
	v_lshlrev_b32_e32 v41, 2, v41
	ds_bpermute_b32 v41, v41, v40
	s_waitcnt lgkmcnt(0)
	v_max_f32_e32 v42, v40, v41
	v_add_f32_e32 v43, 0xc3190000, v157
	v_cmp_lt_f32_e32 vcc, v42, v43
	s_andn2_b64 s[98:99], exec, vcc
	s_cbranch_scc0 .LBB0_120
	v_cmp_gt_f32_e32 vcc, v42, v157
	s_and_b64 s[98:99], exec, vcc
	v_max3_f32 v41, v157, v40, v41
	v_sub_f32_e32 v40, v122, v41
	v_exp_f32_e32 v62, v40
	v_sub_f32_e32 v40, v123, v41
	v_exp_f32_e32 v63, v40
	v_sub_f32_e32 v43, v120, v41
	v_exp_f32_e32 v120, v43
	v_sub_f32_e32 v43, v121, v41
	v_exp_f32_e32 v121, v43
	v_sub_f32_e32 v43, v118, v41
	v_add_f32_e32 v42, 0, v62
	v_exp_f32_e32 v118, v43
	v_sub_f32_e32 v43, v119, v41
	v_add_f32_e32 v42, v63, v42
	v_exp_f32_e32 v119, v43
	v_sub_f32_e32 v43, v54, v41
	v_add_f32_e32 v42, v120, v42
	v_exp_f32_e32 v122, v43
	v_sub_f32_e32 v43, v55, v41
	v_add_f32_e32 v42, v121, v42
	v_exp_f32_e32 v55, v43
	v_sub_f32_e32 v43, v116, v41
	v_add_f32_e32 v42, v118, v42
	v_exp_f32_e32 v116, v43
	v_sub_f32_e32 v43, v117, v41
	v_add_f32_e32 v42, v119, v42
	v_exp_f32_e32 v117, v43
	v_sub_f32_e32 v43, v50, v41
	v_add_f32_e32 v42, v122, v42
	v_exp_f32_e32 v123, v43
	v_sub_f32_e32 v43, v51, v41
	v_sub_f32_e32 v40, v157, v41
	v_add_f32_e32 v42, v55, v42
	v_exp_f32_e32 v157, v43
	v_sub_f32_e32 v43, v124, v41
	v_add_f32_e32 v42, v116, v42
	v_exp_f32_e32 v124, v43
	v_sub_f32_e32 v43, v125, v41
	v_add_f32_e32 v42, v117, v42
	v_exp_f32_e32 v125, v43
	v_add_f32_e32 v42, v123, v42
	v_add_f32_e32 v42, v157, v42
	v_add_f32_e32 v42, v124, v42
	v_add_f32_e32 v44, v125, v42
	v_sub_f32_e32 v42, v60, v41
	v_exp_f32_e32 v60, v42
	v_sub_f32_e32 v42, v61, v41
	v_exp_f32_e32 v61, v42
	v_sub_f32_e32 v42, v58, v41
	v_exp_f32_e32 v42, v42
	v_sub_f32_e32 v43, v59, v41
	v_exp_f32_e32 v43, v43
	v_add_f32_e32 v44, v60, v44
	v_add_f32_e32 v44, v61, v44
	v_add_f32_e32 v44, v42, v44
	v_add_f32_e32 v50, v43, v44
	v_sub_f32_e32 v44, v52, v41
	v_exp_f32_e32 v44, v44
	v_sub_f32_e32 v45, v53, v41
	v_exp_f32_e32 v45, v45
	v_sub_f32_e32 v46, v56, v41
	v_exp_f32_e32 v46, v46
	v_sub_f32_e32 v47, v57, v41
	v_exp_f32_e32 v47, v47
	v_add_f32_e32 v50, v44, v50
	v_add_f32_e32 v50, v45, v50
	v_sub_f32_e32 v48, v48, v41
	v_add_f32_e32 v50, v46, v50
	v_exp_f32_e32 v160, v48
	v_sub_f32_e32 v48, v49, v41
	v_add_f32_e32 v159, v47, v50
	v_exp_f32_e32 v161, v48
	ds_read_b128 v[48:51], v152 offset:27904
	ds_read_b128 v[56:59], v152 offset:32512
	v_exp_f32_e32 v40, v40
	v_cvt_pk_bf16_f32 v52, v62, v63
	v_cvt_pk_bf16_f32 v53, v120, v121
	v_cvt_pk_bf16_f32 v54, v118, v119
	v_cvt_pk_bf16_f32 v55, v122, v55
	v_sub_f32_e32 v38, v38, v41
	s_cmp_eq_u64 s[98:99], 0
	s_cbranch_scc1 .Lnr1b
	v_pk_mul_f32 v[14:15], v[14:15], v[40:41] op_sel_hi:[1,0]
	v_pk_mul_f32 v[12:13], v[12:13], v[40:41] op_sel_hi:[1,0]
	v_pk_mul_f32 v[10:11], v[10:11], v[40:41] op_sel_hi:[1,0]
	v_pk_mul_f32 v[8:9], v[8:9], v[40:41] op_sel_hi:[1,0]
	v_pk_mul_f32 v[6:7], v[6:7], v[40:41] op_sel_hi:[1,0]
	v_pk_mul_f32 v[4:5], v[4:5], v[40:41] op_sel_hi:[1,0]
	v_pk_mul_f32 v[2:3], v[2:3], v[40:41] op_sel_hi:[1,0]
	v_pk_mul_f32 v[0:1], v[0:1], v[40:41] op_sel_hi:[1,0]
	v_pk_mul_f32 v[30:31], v[30:31], v[40:41] op_sel_hi:[1,0]
	v_pk_mul_f32 v[28:29], v[28:29], v[40:41] op_sel_hi:[1,0]
; __device__ __forceinline__ unsigned pk_bf16(float lo, float hi) { unsigned r; asm("v_cvt_pk_bf16_f32 %0, %1, %2" : "=v"(r) : "v"(lo), "v"(hi)); return r; }
; __device__ void attn_item(const Params& p, int s_idx, char* smem) {
;     ...
;             for (int g = 0; g < 4; ++g) {
;                 bf16x8 pf;
;                 {
;                     const unsigned u0 = pk_bf16(sv[g * 8 + 0], sv[g * 8 + 1]), u1 = pk_bf16(sv[g * 8 + 2], sv[g * 8 + 3]);
;                     const unsigned u2 = pk_bf16(sv[g * 8 + 4], sv[g * 8 + 5]), u3 = pk_bf16(sv[g * 8 + 6], sv[g * 8 + 7]);
;                     const uint4 uu = {u0, u1, u2, u3};
;                     pf = __builtin_bit_cast(bf16x8, uu);
;                 }
;                 const int koff = (g >> 1) * 32 + (g & 1) * 16 + 8 * hh;
;                 const bf16x8 v0 = *(const bf16x8*)(sVt + ql * 72 + koff);
;                 const bf16x8 v1 = *(const bf16x8*)(sVt + (32 + ql) * 72 + koff);
;                 O0 = __builtin_amdgcn_mfma_f32_32x32x16_bf16(v0, pf, O0, 0, 0, 0);
;                 O1 = __builtin_amdgcn_mfma_f32_32x32x16_bf16(v1, pf, O1, 0, 0, 0);
;             }
;         }
;     };
;     gload(0, sa); sstore(0, sa); __syncthreads();
;     for (int kt = 0; kt < nkt; kt += 2) {
;         gload(kt + 1, sa);
;         compute(kt, 0);
;         sstore(1, sa);
;         __syncthreads();
;         gload(min(kt + 2, nkt - 1), sa);
;         compute(kt + 1, 1);
;         if (kt + 2 < nkt) sstore(0, sa);
.Lnr1b:
	s_waitcnt lgkmcnt(1)
	v_mfma_f32_32x32x16_bf16 v[0:15], v[48:51], v[52:55], v[0:15]
	ds_read_b128 v[48:51], v152 offset:27936
	s_cmp_eq_u64 s[98:99], 0
	s_cbranch_scc1 .Lnr2b
	v_mul_f32_e64 v26, v26, v40
	v_mul_f32_e64 v27, v27, v40
	v_mul_f32_e64 v24, v24, v40
	v_mul_f32_e64 v25, v25, v40
	v_pk_mul_f32 v[22:23], v[22:23], v[40:41] op_sel_hi:[1,0]
	v_pk_mul_f32 v[20:21], v[20:21], v[40:41] op_sel_hi:[1,0]
	v_pk_mul_f32 v[18:19], v[18:19], v[40:41] op_sel_hi:[1,0]
	v_pk_mul_f32 v[16:17], v[16:17], v[40:41] op_sel_hi:[1,0]
.Lnr2b:
	v_exp_f32_e32 v38, v38
	v_sub_f32_e32 v39, v39, v41
	s_waitcnt lgkmcnt(1)
	v_mfma_f32_32x32x16_bf16 v[16:31], v[56:59], v[52:55], v[16:31]
	ds_read_b128 v[56:59], v152 offset:32544
	v_exp_f32_e32 v39, v39
	v_cvt_pk_bf16_f32 v52, v116, v117
	v_cvt_pk_bf16_f32 v53, v123, v157
	v_cvt_pk_bf16_f32 v54, v124, v125
	v_cvt_pk_bf16_f32 v55, v60, v61
	v_sub_f32_e32 v34, v34, v41
	s_waitcnt lgkmcnt(1)
	v_mfma_f32_32x32x16_bf16 v[0:15], v[48:51], v[52:55], v[0:15]
	v_add_f32_e32 v48, v160, v159
	v_add_f32_e32 v48, v161, v48
	v_add_f32_e32 v48, v38, v48
	v_add_f32_e32 v60, v39, v48
	ds_read_b128 v[48:51], v152 offset:27968
	v_exp_f32_e32 v61, v34
	v_sub_f32_e32 v34, v35, v41
	s_waitcnt lgkmcnt(1)
	v_mfma_f32_32x32x16_bf16 v[16:31], v[56:59], v[52:55], v[16:31]
	ds_read_b128 v[52:55], v152 offset:32576
	v_exp_f32_e32 v56, v34
	v_sub_f32_e32 v34, v36, v41
	v_cvt_pk_bf16_f32 v42, v42, v43
	v_cvt_pk_bf16_f32 v43, v44, v45
	v_cvt_pk_bf16_f32 v44, v46, v47
	v_cvt_pk_bf16_f32 v45, v160, v161
	v_sub_f32_e32 v32, v32, v41
	s_waitcnt lgkmcnt(1)
	v_mfma_f32_32x32x16_bf16 v[0:15], v[48:51], v[42:45], v[0:15]
	v_exp_f32_e32 v50, v34
	v_sub_f32_e32 v34, v37, v41
	v_exp_f32_e32 v51, v34
	ds_read_b128 v[34:37], v152 offset:28000
	ds_read_b128 v[46:49], v152 offset:32608
	v_sub_f32_e32 v33, v33, v41
	v_exp_f32_e32 v32, v32
	s_waitcnt lgkmcnt(2)
	v_mfma_f32_32x32x16_bf16 v[16:31], v[52:55], v[42:45], v[16:31]
	v_exp_f32_e32 v33, v33
	v_cvt_pk_bf16_f32 v42, v38, v39
	v_cvt_pk_bf16_f32 v43, v61, v56
	v_cvt_pk_bf16_f32 v44, v50, v51
	v_cvt_pk_bf16_f32 v45, v32, v33
	v_mov_b32_e32 v157, v41
	s_waitcnt lgkmcnt(1)
	v_mfma_f32_32x32x16_bf16 v[0:15], v[34:37], v[42:45], v[0:15]
	v_add_f32_e32 v34, v61, v60
	v_add_f32_e32 v34, v56, v34
	v_add_f32_e32 v34, v50, v34
	v_add_f32_e32 v34, v51, v34
	v_add_f32_e32 v32, v32, v34
	v_add_f32_e32 v32, v33, v32
	v_fmac_f32_e32 v32, v156, v40
	s_waitcnt lgkmcnt(0)
	v_mfma_f32_32x32x16_bf16 v[16:31], v[46:49], v[42:45], v[16:31]
	v_mov_b32_e32 v156, v32
.LBB0_120:
	s_or_b64 exec, exec, s[36:37]
	s_cmp_le_u32 s16, 1
	s_cselect_b64 s[36:37], -1, 0
	s_and_b64 vcc, exec, s[36:37]
	s_cbranch_vccnz .LBB0_124
	s_waitcnt vmcnt(4)
	ds_write_b128 v106, v[92:95]
	s_waitcnt vmcnt(3)
	ds_write_b16 v107, v84 offset:9216
	ds_write_b16_d16_hi v107, v84 offset:9360
	ds_write_b16 v107, v85 offset:9504
	ds_write_b16_d16_hi v107, v85 offset:9648
	ds_write_b16 v107, v86 offset:9792
	ds_write_b16_d16_hi v107, v86 offset:9936
	ds_write_b16 v107, v87 offset:10080
	ds_write_b16_d16_hi v107, v87 offset:10224
	s_waitcnt vmcnt(2)
	ds_write_b128 v108, v[88:91]
	s_waitcnt vmcnt(1)
	ds_write_b16 v109, v80 offset:9216
	ds_write_b16_d16_hi v109, v80 offset:9360
	ds_write_b16 v109, v81 offset:9504
	ds_write_b16_d16_hi v109, v81 offset:9648
	ds_write_b16 v109, v82 offset:9792
	ds_write_b16_d16_hi v109, v82 offset:9936
	ds_write_b16 v109, v83 offset:10080
	ds_write_b16_d16_hi v109, v83 offset:10224
	s_and_saveexec_b64 s[24:25], s[40:41]
	s_cbranch_execz .LBB0_123
	s_waitcnt vmcnt(0)
	ds_write_b32 v147, v158 offset:18432

; __device__ void attn_item(const Params& p, int s_idx, char* smem) {
;     ...
;     for (int kt = 0; kt < nkt; kt += 2) {
;         gload(kt + 1, sa);
;         compute(kt, 0);
;         sstore(1, sa);
;         __syncthreads();
;         gload(min(kt + 2, nkt - 1), sa);
;         compute(kt + 1, 1);
;         if (kt + 2 < nkt) sstore(0, sa);
;         __syncthreads();
;     }
.LBB0_124:
	s_andn2_b64 vcc, exec, s[36:37]
	s_addk_i32 s20, 0xff80
	s_waitcnt lgkmcnt(0)
	s_barrier
	s_cbranch_vccz .LBB0_126
	s_mov_b32 s16, s17
	s_branch .LBB0_110
